# stack: + P7 epilogue base rows prefetched, P5 near-block bias offsets as immediates, accumulator zeroing with 64-bit moves
# speedup vs baseline: 1.0020x; 1.0017x over previous
;     __device__ bool next(int i, Unit& u) const { if (i > 1 || !so.next(0, u)) return false; if (i == 1) { u.pm += 64; u.pn += 4; } return true; }
; template <class Epi, class Sched, bool ALIGN_EPI = false, bool SP2 = false>
; __device__ __forceinline__ void gemm_phase(PG8_LAS unsigned char* lds, const Gemm g, const Sched& S, const Epi& E) {
;     ...
;         const bool has_next = S.next(ui + 1, nxt);
;         const char* nA = has_next ? (const char*)g.A + (size_t)nxt.pm * tstep : cA; const char* nB = has_next ? (const char*)g.Bt + (size_t)nxt.pn * tstep : cB;
;     ...
;         for (int a = 0; a < 2; ++a)
; #pragma unroll
;             for (int b = 0; b < 2; ++b)
; #pragma unroll
;                 for (int m = 0; m < 4; ++m)
; #pragma unroll
;                     for (int n = 0; n < 2; ++n) acc[a][b][m][n] = (f32x4){0.f, 0.f, 0.f, 0.f};
.LBB0_193:
	s_ashr_i32 s19, s18, 31
	s_lshl_b64 s[20:21], s[18:19], 19
	s_add_u32 s20, s30, s20
	s_addc_u32 s21, s31, s21
	s_and_b64 s[34:35], s[4:5], exec
	s_cselect_b32 s19, s21, s39
	s_cselect_b32 s72, s20, s38
	s_ashr_i32 s17, s16, 31
	s_lshl_b64 s[34:35], s[16:17], 19
	s_add_u32 s34, s88, s34
	s_addc_u32 s35, s89, s35
	s_and_b64 s[52:53], s[4:5], exec
	s_cselect_b32 s17, s35, s41
	s_cselect_b32 s73, s34, s40
	s_add_u32 s38, s38, 0x40080
	s_addc_u32 s39, s39, 0
	s_add_u32 s76, s40, 0x100
	v_mov_b32_e32 v0, 0
	s_addc_u32 s77, s41, 0
	s_mov_b32 s78, -2
	v_mov_b32_e32 v1, v0
	v_mov_b64_e32 v[2:3], 0
	v_mov_b64_e32 v[8:9], 0
	v_mov_b64_e32 v[10:11], 0
	v_mov_b64_e32 v[16:17], 0
	v_mov_b64_e32 v[18:19], 0
	v_mov_b64_e32 v[24:25], 0
	v_mov_b64_e32 v[26:27], 0
	v_mov_b64_e32 v[32:33], 0
	v_mov_b64_e32 v[34:35], 0
	v_mov_b64_e32 v[40:41], 0
	v_mov_b64_e32 v[42:43], 0
	v_mov_b64_e32 v[48:49], 0
	v_mov_b64_e32 v[50:51], 0
	v_mov_b64_e32 v[56:57], 0
	v_mov_b64_e32 v[58:59], 0
	v_mov_b64_e32 v[4:5], 0
	v_mov_b64_e32 v[6:7], 0
	v_mov_b64_e32 v[12:13], 0
	v_mov_b64_e32 v[14:15], 0
	v_mov_b64_e32 v[20:21], 0
	v_mov_b64_e32 v[22:23], 0
	v_mov_b64_e32 v[28:29], 0
	v_mov_b64_e32 v[30:31], 0
	v_mov_b64_e32 v[36:37], 0
	v_mov_b64_e32 v[38:39], 0
	v_mov_b64_e32 v[44:45], 0
	v_mov_b64_e32 v[46:47], 0
	v_mov_b64_e32 v[52:53], 0
	v_mov_b64_e32 v[54:55], 0
	v_mov_b64_e32 v[60:61], 0
	v_mov_b64_e32 v[62:63], 0
	v_mov_b64_e32 v[64:65], 0
	v_mov_b64_e32 v[66:67], 0
	v_mov_b64_e32 v[72:73], 0
	v_mov_b64_e32 v[74:75], 0
	v_mov_b64_e32 v[80:81], 0
	v_mov_b64_e32 v[82:83], 0
	v_mov_b64_e32 v[88:89], 0
	v_mov_b64_e32 v[90:91], 0
	v_mov_b64_e32 v[96:97], 0
	v_mov_b64_e32 v[98:99], 0
	v_mov_b64_e32 v[104:105], 0
	v_mov_b64_e32 v[106:107], 0
	v_mov_b64_e32 v[112:113], 0
	v_mov_b64_e32 v[114:115], 0
	v_mov_b64_e32 v[120:121], 0
	v_mov_b64_e32 v[122:123], 0
	v_mov_b64_e32 v[68:69], 0
	v_mov_b64_e32 v[70:71], 0
	v_mov_b64_e32 v[76:77], 0
	v_mov_b64_e32 v[78:79], 0
	v_mov_b64_e32 v[84:85], 0
	v_mov_b64_e32 v[86:87], 0
	v_mov_b64_e32 v[92:93], 0
	v_mov_b64_e32 v[94:95], 0
	v_mov_b64_e32 v[100:101], 0
	v_mov_b64_e32 v[102:103], 0
	v_mov_b64_e32 v[108:109], 0
	v_mov_b64_e32 v[110:111], 0
	v_mov_b64_e32 v[116:117], 0
	v_mov_b64_e32 v[118:119], 0
	v_mov_b64_e32 v[124:125], 0
	v_mov_b64_e32 v[126:127], 0

; template <class Epi, class Sched, bool ALIGN_EPI = false, bool SP2 = false>
; __device__ __forceinline__ void gemm_phase(PG8_LAS unsigned char* lds, const Gemm g, const Sched& S, const Epi& E) {
;     ...
;         for (int a = 0; a < 2; ++a)
; #pragma unroll
;             for (int b = 0; b < 2; ++b)
; #pragma unroll
;                 for (int m = 0; m < 4; ++m)
; #pragma unroll
;                     for (int n = 0; n < 2; ++n) acc[a][b][m][n] = (f32x4){0.f, 0.f, 0.f, 0.f};
.LBB0_288:
	s_add_u32 s22, s22, 0xb0080
	s_addc_u32 s23, s23, 0
	s_add_u32 s66, s34, 0x100
	v_mov_b32_e32 v0, 0
	s_addc_u32 s67, s35, 0
	s_mov_b32 s70, -2
	s_waitcnt lgkmcnt(0)
	v_mov_b32_e32 v1, v0
	v_mov_b64_e32 v[2:3], 0
	v_mov_b64_e32 v[4:5], 0
	v_mov_b64_e32 v[6:7], 0
	v_mov_b64_e32 v[16:17], 0
	v_mov_b64_e32 v[18:19], 0
	v_mov_b64_e32 v[20:21], 0
	v_mov_b64_e32 v[22:23], 0
	v_mov_b64_e32 v[32:33], 0
	v_mov_b64_e32 v[34:35], 0
	v_mov_b64_e32 v[36:37], 0
	v_mov_b64_e32 v[38:39], 0
	v_mov_b64_e32 v[48:49], 0
	v_mov_b64_e32 v[50:51], 0
	v_mov_b64_e32 v[52:53], 0
	v_mov_b64_e32 v[54:55], 0
	v_mov_b64_e32 v[8:9], 0
	v_mov_b64_e32 v[10:11], 0
	v_mov_b64_e32 v[12:13], 0
	v_mov_b64_e32 v[14:15], 0
	v_mov_b64_e32 v[24:25], 0
	v_mov_b64_e32 v[26:27], 0
	v_mov_b64_e32 v[28:29], 0
	v_mov_b64_e32 v[30:31], 0
	v_mov_b64_e32 v[40:41], 0
	v_mov_b64_e32 v[42:43], 0
	v_mov_b64_e32 v[44:45], 0
	v_mov_b64_e32 v[46:47], 0
	v_mov_b64_e32 v[56:57], 0
	v_mov_b64_e32 v[58:59], 0
	v_mov_b64_e32 v[60:61], 0
	v_mov_b64_e32 v[62:63], 0
	v_mov_b64_e32 v[64:65], 0
	v_mov_b64_e32 v[66:67], 0
	v_mov_b64_e32 v[68:69], 0
	v_mov_b64_e32 v[70:71], 0
	v_mov_b64_e32 v[80:81], 0
	v_mov_b64_e32 v[82:83], 0
	v_mov_b64_e32 v[84:85], 0
	v_mov_b64_e32 v[86:87], 0
	v_mov_b64_e32 v[96:97], 0
	v_mov_b64_e32 v[98:99], 0
	v_mov_b64_e32 v[100:101], 0
	v_mov_b64_e32 v[102:103], 0
	v_mov_b64_e32 v[112:113], 0
	v_mov_b64_e32 v[114:115], 0
	v_mov_b64_e32 v[116:117], 0
	v_mov_b64_e32 v[118:119], 0
	v_mov_b64_e32 v[72:73], 0
	v_mov_b64_e32 v[74:75], 0
	v_mov_b64_e32 v[76:77], 0
	v_mov_b64_e32 v[78:79], 0
	v_mov_b64_e32 v[88:89], 0
	v_mov_b64_e32 v[90:91], 0
	v_mov_b64_e32 v[92:93], 0
	v_mov_b64_e32 v[94:95], 0
	v_mov_b64_e32 v[104:105], 0
	v_mov_b64_e32 v[106:107], 0
	v_mov_b64_e32 v[108:109], 0
	v_mov_b64_e32 v[110:111], 0
	v_mov_b64_e32 v[120:121], 0
	v_mov_b64_e32 v[122:123], 0
	v_mov_b64_e32 v[124:125], 0
	v_mov_b64_e32 v[126:127], 0

; template <class Epi, class Sched, bool ALIGN_EPI = false, bool SP2 = false>
; __device__ __forceinline__ void gemm_phase(PG8_LAS unsigned char* lds, const Gemm g, const Sched& S, const Epi& E) {
;     ...
;         for (int a = 0; a < 2; ++a)
; #pragma unroll
;             for (int b = 0; b < 2; ++b)
; #pragma unroll
;                 for (int m = 0; m < 4; ++m)
; #pragma unroll
;                     for (int n = 0; n < 2; ++n) acc[a][b][m][n] = (f32x4){0.f, 0.f, 0.f, 0.f};
.LBB0_406:
	s_ashr_i32 s41, s40, 31
	s_lshl_b64 s[44:45], s[40:41], 19
	s_add_u32 s44, s84, s44
	s_addc_u32 s45, s85, s45
	s_and_b64 s[46:47], s[4:5], exec
	s_cselect_b32 s7, s45, s1
	s_cselect_b32 s9, s44, s0
	s_ashr_i32 s23, s22, 31
	s_lshl_b64 s[46:47], s[22:23], 19
	s_add_u32 s46, s21, s46
	s_addc_u32 s47, s58, s47
	s_and_b64 s[52:53], s[4:5], exec
	s_cselect_b32 s12, s47, s49
	s_cselect_b32 s23, s46, s48
	s_add_u32 s0, s0, 0x40080
	s_addc_u32 s1, s1, 0
	s_add_u32 s41, s48, 0x100
	v_mov_b32_e32 v0, 0
	s_addc_u32 s54, s49, 0
	s_mov_b32 s55, -2
	v_mov_b32_e32 v1, v0
	v_mov_b64_e32 v[2:3], 0
	v_mov_b64_e32 v[4:5], 0
	v_mov_b64_e32 v[6:7], 0
	v_mov_b64_e32 v[16:17], 0
	v_mov_b64_e32 v[18:19], 0
	v_mov_b64_e32 v[20:21], 0
	v_mov_b64_e32 v[22:23], 0
	v_mov_b64_e32 v[64:65], 0
	v_mov_b64_e32 v[66:67], 0
	v_mov_b64_e32 v[68:69], 0
	v_mov_b64_e32 v[70:71], 0
	v_mov_b64_e32 v[80:81], 0
	v_mov_b64_e32 v[82:83], 0
	v_mov_b64_e32 v[84:85], 0
	v_mov_b64_e32 v[86:87], 0
	v_mov_b64_e32 v[8:9], 0
	v_mov_b64_e32 v[10:11], 0
	v_mov_b64_e32 v[12:13], 0
	v_mov_b64_e32 v[14:15], 0
	v_mov_b64_e32 v[32:33], 0
	v_mov_b64_e32 v[34:35], 0
	v_mov_b64_e32 v[40:41], 0
	v_mov_b64_e32 v[42:43], 0
	v_mov_b64_e32 v[72:73], 0
	v_mov_b64_e32 v[74:75], 0
	v_mov_b64_e32 v[76:77], 0
	v_mov_b64_e32 v[78:79], 0
	v_mov_b64_e32 v[88:89], 0
	v_mov_b64_e32 v[90:91], 0
	v_mov_b64_e32 v[92:93], 0
	v_mov_b64_e32 v[94:95], 0
	v_mov_b64_e32 v[96:97], 0
	v_mov_b64_e32 v[98:99], 0
	v_mov_b64_e32 v[100:101], 0
	v_mov_b64_e32 v[102:103], 0
	v_mov_b64_e32 v[112:113], 0
	v_mov_b64_e32 v[114:115], 0
	v_mov_b64_e32 v[116:117], 0
	v_mov_b64_e32 v[118:119], 0
	v_mov_b64_e32 v[128:129], 0
	v_mov_b64_e32 v[130:131], 0
	v_mov_b64_e32 v[132:133], 0
	v_mov_b64_e32 v[134:135], 0
	v_mov_b64_e32 v[144:145], 0
	v_mov_b64_e32 v[146:147], 0
	v_mov_b64_e32 v[148:149], 0
	v_mov_b64_e32 v[150:151], 0
	v_mov_b64_e32 v[104:105], 0
	v_mov_b64_e32 v[106:107], 0
	v_mov_b64_e32 v[108:109], 0
	v_mov_b64_e32 v[110:111], 0
	v_mov_b64_e32 v[120:121], 0
	v_mov_b64_e32 v[122:123], 0
	v_mov_b64_e32 v[124:125], 0
	v_mov_b64_e32 v[126:127], 0
	v_mov_b64_e32 v[136:137], 0
	v_mov_b64_e32 v[138:139], 0
	v_mov_b64_e32 v[140:141], 0
	v_mov_b64_e32 v[142:143], 0
	v_mov_b64_e32 v[152:153], 0
	v_mov_b64_e32 v[154:155], 0
	v_mov_b64_e32 v[156:157], 0
	v_mov_b64_e32 v[158:159], 0

; template <class Epi, class Sched, bool ALIGN_EPI = false, bool SP2 = false>
; __device__ __forceinline__ void gemm_phase(PG8_LAS unsigned char* lds, const Gemm g, const Sched& S, const Epi& E) {
;     ...
;         for (int a = 0; a < 2; ++a)
; #pragma unroll
;             for (int b = 0; b < 2; ++b)
; #pragma unroll
;                 for (int m = 0; m < 4; ++m)
; #pragma unroll
;                     for (int n = 0; n < 2; ++n) acc[a][b][m][n] = (f32x4){0.f, 0.f, 0.f, 0.f};
.LBB0_807:
	s_ashr_i32 s23, s22, 31
	s_lshl_b64 s[36:37], s[22:23], 19
	s_add_u32 s36, s30, s36
	s_addc_u32 s37, s31, s37
	s_and_b64 s[38:39], s[6:7], exec
	s_cselect_b32 s23, s37, s45
	s_cselect_b32 s41, s36, s44
	s_ashr_i32 s21, s20, 31
	s_lshl_b64 s[38:39], s[20:21], 19
	s_add_u32 s38, s92, s38
	s_addc_u32 s39, s93, s39
	s_and_b64 s[48:49], s[6:7], exec
	s_cselect_b32 s21, s39, s47
	s_cselect_b32 s68, s38, s46
	s_add_u32 s44, s44, 0x40080
	s_addc_u32 s45, s45, 0
	s_add_u32 s69, s46, 0x100
	v_mov_b32_e32 v0, 0
	s_addc_u32 s70, s47, 0
	s_mov_b32 s71, -2
	s_waitcnt lgkmcnt(0)
	v_mov_b32_e32 v1, v0
	v_mov_b64_e32 v[2:3], 0
	v_mov_b64_e32 v[4:5], 0
	v_mov_b64_e32 v[6:7], 0
	v_mov_b64_e32 v[16:17], 0
	v_mov_b64_e32 v[18:19], 0
	v_mov_b64_e32 v[20:21], 0
	v_mov_b64_e32 v[22:23], 0
	v_mov_b64_e32 v[32:33], 0
	v_mov_b64_e32 v[34:35], 0
	v_mov_b64_e32 v[36:37], 0
	v_mov_b64_e32 v[38:39], 0
	v_mov_b64_e32 v[48:49], 0
	v_mov_b64_e32 v[50:51], 0
	v_mov_b64_e32 v[52:53], 0
	v_mov_b64_e32 v[54:55], 0
	v_mov_b64_e32 v[8:9], 0
	v_mov_b64_e32 v[10:11], 0
	v_mov_b64_e32 v[12:13], 0
	v_mov_b64_e32 v[14:15], 0
	v_mov_b64_e32 v[24:25], 0
	v_mov_b64_e32 v[26:27], 0
	v_mov_b64_e32 v[28:29], 0
	v_mov_b64_e32 v[30:31], 0
	v_mov_b64_e32 v[40:41], 0
	v_mov_b64_e32 v[42:43], 0
	v_mov_b64_e32 v[44:45], 0
	v_mov_b64_e32 v[46:47], 0
	v_mov_b64_e32 v[56:57], 0
	v_mov_b64_e32 v[58:59], 0
	v_mov_b64_e32 v[60:61], 0
	v_mov_b64_e32 v[62:63], 0
	v_mov_b64_e32 v[64:65], 0
	v_mov_b64_e32 v[66:67], 0
	v_mov_b64_e32 v[68:69], 0
	v_mov_b64_e32 v[70:71], 0
	v_mov_b64_e32 v[88:89], 0
	v_mov_b64_e32 v[90:91], 0
	v_mov_b64_e32 v[92:93], 0
	v_mov_b64_e32 v[94:95], 0
	v_mov_b64_e32 v[112:113], 0
	v_mov_b64_e32 v[114:115], 0
	v_mov_b64_e32 v[116:117], 0
	v_mov_b64_e32 v[118:119], 0
	v_mov_b64_e32 v[128:129], 0
	v_mov_b64_e32 v[130:131], 0
	v_mov_b64_e32 v[132:133], 0
	v_mov_b64_e32 v[134:135], 0
	v_mov_b64_e32 v[72:73], 0
	v_mov_b64_e32 v[74:75], 0
	v_mov_b64_e32 v[76:77], 0
	v_mov_b64_e32 v[78:79], 0
	v_mov_b64_e32 v[104:105], 0
	v_mov_b64_e32 v[106:107], 0
	v_mov_b64_e32 v[108:109], 0
	v_mov_b64_e32 v[110:111], 0
	v_mov_b64_e32 v[120:121], 0
	v_mov_b64_e32 v[122:123], 0
	v_mov_b64_e32 v[124:125], 0
	v_mov_b64_e32 v[126:127], 0
	v_mov_b64_e32 v[136:137], 0
	v_mov_b64_e32 v[138:139], 0
	v_mov_b64_e32 v[140:141], 0
	v_mov_b64_e32 v[142:143], 0

;     __device__ __forceinline__ void operator()(const f32x4 (&acc)[2][2][4][2], const Unit& u, int wr, int wc, int fr, int fq) const {
;         const float* g = gate + (u.pm >> 5) * 9216;
;         const int row0 = u.pm * BM + wr * 64 + fr, col0 = u.pn * BM + wc * 32 + 8 * fq;
;         f32x4 gv[2][2];
; #pragma unroll
;         for (int bj = 0; bj < 2; ++bj)
; #pragma unroll
;             for (int n = 0; n < 2; ++n) gv[bj][n] = *(const f32x4*)(g + col0 + bj * HALF + 4 * n) * coef;
; #pragma unroll
;         for (int ai = 0; ai < 2; ++ai)
; #pragma unroll
;             for (int m = 0; m < 4; ++m) {
;                 const int row = row0 + ai * HALF + m * 16; const size_t off = (size_t)row * 1024 + col0;
;                 f32x4 b0[2], b1[2];
; #pragma unroll
;                 for (int bj = 0; bj < 2; ++bj) {
;                     if (BASE_BF16) { const u32x4 t = *(const u32x4*)((const bf16_t*)base + off + bj * HALF);
;                         b0[bj] = (f32x4){bf_lo(t.x), bf_hi(t.x), bf_lo(t.y), bf_hi(t.y)}; b1[bj] = (f32x4){bf_lo(t.z), bf_hi(t.z), bf_lo(t.w), bf_hi(t.w)}; }
;                     else { b0[bj] = *(const f32x4*)((const float*)base + off + bj * HALF); b1[bj] = *(const f32x4*)((const float*)base + off + bj * HALF + 4); }
;                 }
;                 float ss = 0.f;
; #pragma unroll
;                 for (int bj = 0; bj < 2; ++bj) {
;                     const f32x4 v0 = b0[bj] + gv[bj][0] * acc[ai][bj][m][0], v1 = b1[bj] + gv[bj][1] * acc[ai][bj][m][1];
;                     if (OUT_BF16) {
;                         u32x4 w; w.x = cvt_pk_bf16(v0[0], v0[1]); w.y = cvt_pk_bf16(v0[2], v0[3]); w.z = cvt_pk_bf16(v1[0], v1[1]); w.w = cvt_pk_bf16(v1[2], v1[3]);
;                         *(u32x4*)((bf16_t*)out + off + bj * HALF) = w;
;                         ss += ((v0[0] * v0[0] + v0[1] * v0[1]) + (v0[2] * v0[2] + v0[3] * v0[3])) + ((v1[0] * v1[0] + v1[1] * v1[1]) + (v1[2] * v1[2] + v1[3] * v1[3]));
;                     } else { *(f32x4*)((float*)out + off + bj * HALF) = v0; *(f32x4*)((float*)out + off + bj * HALF + 4) = v1; }
;                 }
;                 if (OUT_BF16) { ss += __shfl_xor(ss, 16); ss += __shfl_xor(ss, 32); if (fq == 0) rowp[(size_t)row * 16 + u.pn * 4 + wc] = ss; }
;             }
.LBB0_811:
	v_lshl_add_u32 v164, s40, 8, v163
	s_lshr_b32 s21, s40, 5
	v_lshl_or_b32 v160, s12, 8, v167
	v_ashrrev_i32_e32 v165, 31, v164
	s_mul_i32 s40, s21, 0x2400
	v_ashrrev_i32_e32 v161, 31, v160
	v_lshlrev_b64 v[80:81], 10, v[164:165]
	s_ashr_i32 s41, s40, 31
	v_lshl_add_u64 v[80:81], v[80:81], 0, v[160:161]
	s_lshl_b64 s[40:41], s[40:41], 2
	v_lshlrev_b64 v[182:183], 1, v[80:81]
	s_add_u32 s40, s54, s40
	v_lshl_add_u64 v[80:81], s[84:85], 0, v[182:183]
	s_addc_u32 s41, s55, s41
	global_load_dwordx4 v[174:177], v[80:81], off
	global_load_dwordx4 v[178:181], v[80:81], off offset:256
	v_lshl_add_u64 v[80:81], v[160:161], 2, s[40:41]
	global_load_dwordx4 v[100:103], v[80:81], off
	global_load_dwordx4 v[96:99], v[80:81], off offset:16
	global_load_dwordx4 v[84:87], v[80:81], off offset:512
	s_nop 0
	global_load_dwordx4 v[80:83], v[80:81], off offset:528
	v_add_u32_e32 v224, 16, v164
	v_lshl_add_u32 v224, v224, 10, v160
	v_lshlrev_b32_e32 v224, 1, v224
	global_load_dwordx4 v[192:195], v224, s[84:85]
	global_load_dwordx4 v[196:199], v224, s[84:85] offset:256
	v_add_u32_e32 v224, 32, v164
	v_lshl_add_u32 v224, v224, 10, v160
	v_lshlrev_b32_e32 v224, 1, v224
	global_load_dwordx4 v[200:203], v224, s[84:85]
	global_load_dwordx4 v[204:207], v224, s[84:85] offset:256
	v_add_u32_e32 v224, 48, v164
	v_lshl_add_u32 v224, v224, 10, v160
	v_lshlrev_b32_e32 v224, 1, v224
	global_load_dwordx4 v[208:211], v224, s[84:85]
	global_load_dwordx4 v[212:215], v224, s[84:85] offset:256
	v_add_u32_e32 v224, 128, v164
	v_lshl_add_u32 v224, v224, 10, v160
	v_lshlrev_b32_e32 v224, 1, v224
	global_load_dwordx4 v[216:219], v224, s[84:85]
	global_load_dwordx4 v[220:223], v224, s[84:85] offset:256
	v_add_u32_e32 v224, 144, v164
	v_lshl_add_u32 v224, v224, 10, v160
	v_lshlrev_b32_e32 v224, 1, v224
	global_load_dwordx4 v[228:231], v224, s[84:85]
	global_load_dwordx4 v[232:235], v224, s[84:85] offset:256
	v_add_u32_e32 v224, 160, v164
	v_lshl_add_u32 v224, v224, 10, v160
	v_lshlrev_b32_e32 v224, 1, v224
	global_load_dwordx4 v[236:239], v224, s[84:85]
	global_load_dwordx4 v[240:243], v224, s[84:85] offset:256
	v_add_u32_e32 v224, 176, v164
	v_lshl_add_u32 v224, v224, 10, v160
	v_lshlrev_b32_e32 v224, 1, v224
	global_load_dwordx4 v[244:247], v224, s[84:85]
	global_load_dwordx4 v[248:251], v224, s[84:85] offset:256
	v_and_b32_e32 v173, 64, v171
	v_xor_b32_e32 v172, 16, v171
	v_add_u32_e32 v173, 64, v173
	v_xor_b32_e32 v184, 32, v171
	v_cmp_lt_i32_e32 vcc, v172, v173
	s_lshl_b32 s40, s12, 2
	s_ashr_i32 s41, s40, 31
	v_cndmask_b32_e32 v172, v171, v172, vcc
	v_cmp_lt_i32_e32 vcc, v184, v173
	v_lshlrev_b32_e32 v173, 2, v172
	s_waitcnt vmcnt(14)
	v_and_b32_e32 v185, 0xffff0000, v174
	v_cndmask_b32_e32 v184, v171, v184, vcc
	v_lshlrev_b32_e32 v172, 2, v184
	v_lshlrev_b32_e32 v184, 16, v174
	v_lshlrev_b32_e32 v174, 16, v175
	v_and_b32_e32 v175, 0xffff0000, v175
	v_lshlrev_b32_e32 v186, 16, v176
	v_and_b32_e32 v187, 0xffff0000, v176
	v_lshlrev_b32_e32 v176, 16, v177
	v_and_b32_e32 v177, 0xffff0000, v177
	v_lshlrev_b32_e32 v188, 16, v178
	v_and_b32_e32 v189, 0xffff0000, v178
	v_lshlrev_b32_e32 v178, 16, v179
	v_and_b32_e32 v179, 0xffff0000, v179
	v_lshlrev_b32_e32 v190, 16, v180
	v_and_b32_e32 v191, 0xffff0000, v180
	v_lshlrev_b32_e32 v180, 16, v181
	v_and_b32_e32 v181, 0xffff0000, v181
	v_pk_fma_f32 v[142:143], v[142:143], v[102:103], v[174:175]
	v_pk_fma_f32 v[140:141], v[140:141], v[100:101], v[184:185]
	v_pk_fma_f32 v[138:139], v[138:139], v[98:99], v[176:177]
	v_pk_fma_f32 v[136:137], v[136:137], v[96:97], v[186:187]
	v_pk_fma_f32 v[134:135], v[134:135], v[86:87], v[178:179]
	v_pk_fma_f32 v[132:133], v[132:133], v[84:85], v[188:189]
	v_pk_fma_f32 v[174:175], v[130:131], v[82:83], v[180:181]
	v_pk_fma_f32 v[176:177], v[128:129], v[80:81], v[190:191]
	v_cvt_pk_bf16_f32 v128, v140, v141
	v_cvt_pk_bf16_f32 v129, v142, v143
	v_cvt_pk_bf16_f32 v130, v136, v137
	v_mul_f32_e32 v131, v141, v141
	v_mul_f32_e32 v141, v143, v143
	v_mul_f32_e32 v137, v137, v137
	v_mul_f32_e32 v143, v139, v139
	v_mul_f32_e32 v178, v133, v133
	v_mul_f32_e32 v179, v135, v135
	v_mul_f32_e32 v180, v177, v177
	v_mul_f32_e32 v181, v175, v175
	v_fmac_f32_e32 v131, v140, v140
	v_fmac_f32_e32 v141, v142, v142
	v_fmac_f32_e32 v137, v136, v136
	v_fmac_f32_e32 v143, v138, v138
	v_fmac_f32_e32 v178, v132, v132
	v_fmac_f32_e32 v179, v134, v134
	v_fmac_f32_e32 v180, v176, v176
	v_fmac_f32_e32 v181, v174, v174
	v_add_f32_e32 v131, v131, v141
	v_add_f32_e32 v136, v137, v143
	v_add_f32_e32 v137, v178, v179
	v_add_f32_e32 v140, v180, v181
	v_add_f32_e32 v131, v131, v136
	v_add_f32_e32 v136, v137, v140
	v_add_f32_e32 v140, v131, v136
	ds_bpermute_b32 v141, v173, v140
	v_cvt_pk_bf16_f32 v131, v138, v139
	v_lshl_add_u64 v[136:137], s[24:25], 0, v[182:183]
	global_store_dwordx4 v[136:137], v[128:131], off
	s_waitcnt lgkmcnt(0)
	s_nop 0
	v_add_f32_e32 v128, v140, v141
	ds_bpermute_b32 v129, v172, v128
	v_cvt_pk_bf16_f32 v130, v132, v133
	v_cvt_pk_bf16_f32 v131, v134, v135
	v_cvt_pk_bf16_f32 v132, v176, v177
	v_cvt_pk_bf16_f32 v133, v174, v175
	global_store_dwordx4 v[136:137], v[130:133], off offset:256
	s_and_saveexec_b64 s[44:45], s[4:5]
	s_cbranch_execz .LBB0_813
	s_waitcnt lgkmcnt(0)
	v_add_f32_e32 v130, v128, v129
	v_lshlrev_b64 v[128:129], 6, v[164:165]
	v_lshl_add_u64 v[128:129], s[0:1], 0, v[128:129]
	v_lshl_add_u64 v[128:129], s[40:41], 2, v[128:129]
	s_lshl_b32 s12, s56, 2
	v_lshl_add_u64 v[128:129], v[128:129], 0, s[12:13]
	global_store_dword v[128:129], v130, off
;     __device__ __forceinline__ void operator()(const f32x4 (&acc)[2][2][4][2], const Unit& u, int wr, int wc, int fr, int fq) const {
;         const float* g = gate + (u.pm >> 5) * 9216;
;         const int row0 = u.pm * BM + wr * 64 + fr, col0 = u.pn * BM + wc * 32 + 8 * fq;
;         f32x4 gv[2][2];
; #pragma unroll
;         for (int bj = 0; bj < 2; ++bj)
; #pragma unroll
;             for (int n = 0; n < 2; ++n) gv[bj][n] = *(const f32x4*)(g + col0 + bj * HALF + 4 * n) * coef;
; #pragma unroll
;         for (int ai = 0; ai < 2; ++ai)
; #pragma unroll
;             for (int m = 0; m < 4; ++m) {
;                 const int row = row0 + ai * HALF + m * 16; const size_t off = (size_t)row * 1024 + col0;
;                 f32x4 b0[2], b1[2];
; #pragma unroll
;                 for (int bj = 0; bj < 2; ++bj) {
;                     if (BASE_BF16) { const u32x4 t = *(const u32x4*)((const bf16_t*)base + off + bj * HALF);
;                         b0[bj] = (f32x4){bf_lo(t.x), bf_hi(t.x), bf_lo(t.y), bf_hi(t.y)}; b1[bj] = (f32x4){bf_lo(t.z), bf_hi(t.z), bf_lo(t.w), bf_hi(t.w)}; }
;                     else { b0[bj] = *(const f32x4*)((const float*)base + off + bj * HALF); b1[bj] = *(const f32x4*)((const float*)base + off + bj * HALF + 4); }
;                 }
;                 float ss = 0.f;
; #pragma unroll
;                 for (int bj = 0; bj < 2; ++bj) {
;                     const f32x4 v0 = b0[bj] + gv[bj][0] * acc[ai][bj][m][0], v1 = b1[bj] + gv[bj][1] * acc[ai][bj][m][1];
;                     if (OUT_BF16) {
;                         u32x4 w; w.x = cvt_pk_bf16(v0[0], v0[1]); w.y = cvt_pk_bf16(v0[2], v0[3]); w.z = cvt_pk_bf16(v1[0], v1[1]); w.w = cvt_pk_bf16(v1[2], v1[3]);
;                         *(u32x4*)((bf16_t*)out + off + bj * HALF) = w;
;                         ss += ((v0[0] * v0[0] + v0[1] * v0[1]) + (v0[2] * v0[2] + v0[3] * v0[3])) + ((v1[0] * v1[0] + v1[1] * v1[1]) + (v1[2] * v1[2] + v1[3] * v1[3]));
;                     } else { *(f32x4*)((float*)out + off + bj * HALF) = v0; *(f32x4*)((float*)out + off + bj * HALF + 4) = v1; }
;                 }
;                 if (OUT_BF16) { ss += __shfl_xor(ss, 16); ss += __shfl_xor(ss, 32); if (fq == 0) rowp[(size_t)row * 16 + u.pn * 4 + wc] = ss; }
;             }
.LBB0_813:
	s_or_b64 exec, exec, s[44:45]
	v_or_b32_e32 v128, 16, v164
	s_waitcnt lgkmcnt(0)
	v_ashrrev_i32_e32 v129, 31, v128
	v_lshlrev_b64 v[130:131], 10, v[128:129]
	v_lshl_add_u64 v[130:131], v[130:131], 0, v[160:161]
	v_lshlrev_b64 v[138:139], 1, v[130:131]
	v_lshl_add_u64 v[134:135], s[84:85], 0, v[138:139]
	s_waitcnt vmcnt(14)
	v_mov_b32_e32 v130, v192
	v_mov_b32_e32 v131, v193
	v_mov_b32_e32 v132, v194
	v_mov_b32_e32 v133, v195
	v_mov_b32_e32 v134, v196
	v_mov_b32_e32 v135, v197
	v_mov_b32_e32 v136, v198
	v_mov_b32_e32 v137, v199
	v_lshlrev_b32_e32 v140, 16, v130
	v_and_b32_e32 v141, 0xffff0000, v130
	v_lshlrev_b32_e32 v130, 16, v131
	v_and_b32_e32 v131, 0xffff0000, v131
	v_lshlrev_b32_e32 v142, 16, v132
	v_and_b32_e32 v143, 0xffff0000, v132
	v_lshlrev_b32_e32 v132, 16, v133
	v_and_b32_e32 v133, 0xffff0000, v133
	v_lshlrev_b32_e32 v174, 16, v134
	v_and_b32_e32 v175, 0xffff0000, v134
	v_lshlrev_b32_e32 v134, 16, v135
	v_and_b32_e32 v135, 0xffff0000, v135
	v_lshlrev_b32_e32 v176, 16, v136
	v_and_b32_e32 v177, 0xffff0000, v136
	v_lshlrev_b32_e32 v136, 16, v137
	v_and_b32_e32 v137, 0xffff0000, v137
	v_pk_fma_f32 v[126:127], v[126:127], v[102:103], v[130:131]
	v_pk_fma_f32 v[124:125], v[124:125], v[100:101], v[140:141]
	v_pk_fma_f32 v[122:123], v[122:123], v[98:99], v[132:133]
	v_pk_fma_f32 v[120:121], v[120:121], v[96:97], v[142:143]
	v_pk_fma_f32 v[118:119], v[118:119], v[86:87], v[134:135]
	v_pk_fma_f32 v[116:117], v[116:117], v[84:85], v[174:175]
	v_pk_fma_f32 v[130:131], v[114:115], v[82:83], v[136:137]
	v_pk_fma_f32 v[132:133], v[112:113], v[80:81], v[176:177]
	v_cvt_pk_bf16_f32 v112, v124, v125
	v_cvt_pk_bf16_f32 v113, v126, v127
	v_cvt_pk_bf16_f32 v114, v120, v121
	v_mul_f32_e32 v115, v125, v125
	v_mul_f32_e32 v125, v127, v127
	v_mul_f32_e32 v121, v121, v121
	v_mul_f32_e32 v127, v123, v123
	v_mul_f32_e32 v134, v117, v117
	v_mul_f32_e32 v135, v119, v119
	v_mul_f32_e32 v136, v133, v133
	v_mul_f32_e32 v137, v131, v131
	v_fmac_f32_e32 v115, v124, v124
	v_fmac_f32_e32 v125, v126, v126
	v_fmac_f32_e32 v121, v120, v120
	v_fmac_f32_e32 v127, v122, v122
	v_fmac_f32_e32 v134, v116, v116
	v_fmac_f32_e32 v135, v118, v118
	v_fmac_f32_e32 v136, v132, v132
	v_fmac_f32_e32 v137, v130, v130
	v_add_f32_e32 v115, v115, v125
	v_add_f32_e32 v120, v121, v127
	v_add_f32_e32 v121, v134, v135
	v_add_f32_e32 v124, v136, v137
	v_add_f32_e32 v115, v115, v120
	v_add_f32_e32 v120, v121, v124
	v_add_f32_e32 v124, v115, v120
	ds_bpermute_b32 v125, v173, v124
	v_cvt_pk_bf16_f32 v115, v122, v123
	v_lshl_add_u64 v[120:121], s[24:25], 0, v[138:139]
	global_store_dwordx4 v[120:121], v[112:115], off
	s_waitcnt lgkmcnt(0)
	s_nop 0
	v_add_f32_e32 v112, v124, v125
	ds_bpermute_b32 v113, v172, v112
	v_cvt_pk_bf16_f32 v114, v116, v117
	v_cvt_pk_bf16_f32 v115, v118, v119
	v_cvt_pk_bf16_f32 v116, v132, v133
	v_cvt_pk_bf16_f32 v117, v130, v131
	global_store_dwordx4 v[120:121], v[114:117], off offset:256
	s_and_saveexec_b64 s[44:45], s[4:5]
	s_cbranch_execz .LBB0_815
	s_waitcnt lgkmcnt(0)
	v_add_f32_e32 v114, v112, v113
	v_lshlrev_b64 v[112:113], 6, v[128:129]
	v_lshl_add_u64 v[112:113], s[0:1], 0, v[112:113]
	v_lshl_add_u64 v[112:113], s[40:41], 2, v[112:113]
	s_lshl_b32 s12, s56, 2
	v_lshl_add_u64 v[112:113], v[112:113], 0, s[12:13]
	global_store_dword v[112:113], v114, off
.LBB0_815:
	s_or_b64 exec, exec, s[44:45]
	v_or_b32_e32 v112, 32, v164
	s_waitcnt lgkmcnt(0)
	v_ashrrev_i32_e32 v113, 31, v112
	v_lshlrev_b64 v[114:115], 10, v[112:113]
	v_lshl_add_u64 v[114:115], v[114:115], 0, v[160:161]
	v_lshlrev_b64 v[122:123], 1, v[114:115]
	v_lshl_add_u64 v[118:119], s[84:85], 0, v[122:123]
	s_waitcnt vmcnt(14)
	v_mov_b32_e32 v114, v200
	v_mov_b32_e32 v115, v201
	v_mov_b32_e32 v116, v202
	v_mov_b32_e32 v117, v203
	v_mov_b32_e32 v118, v204
	v_mov_b32_e32 v119, v205
	v_mov_b32_e32 v120, v206
	v_mov_b32_e32 v121, v207
	v_lshlrev_b32_e32 v124, 16, v114
	v_and_b32_e32 v125, 0xffff0000, v114
	v_lshlrev_b32_e32 v114, 16, v115
	v_and_b32_e32 v115, 0xffff0000, v115
	v_lshlrev_b32_e32 v126, 16, v116
	v_and_b32_e32 v127, 0xffff0000, v116
	v_lshlrev_b32_e32 v116, 16, v117
	v_and_b32_e32 v117, 0xffff0000, v117
	v_lshlrev_b32_e32 v128, 16, v118
	v_and_b32_e32 v129, 0xffff0000, v118
	v_lshlrev_b32_e32 v118, 16, v119
	v_and_b32_e32 v119, 0xffff0000, v119
	v_lshlrev_b32_e32 v130, 16, v120
	v_and_b32_e32 v131, 0xffff0000, v120
	v_lshlrev_b32_e32 v120, 16, v121
	v_and_b32_e32 v121, 0xffff0000, v121
	v_pk_fma_f32 v[110:111], v[110:111], v[102:103], v[114:115]
	v_pk_fma_f32 v[108:109], v[108:109], v[100:101], v[124:125]
	v_pk_fma_f32 v[106:107], v[106:107], v[98:99], v[116:117]
	v_pk_fma_f32 v[104:105], v[104:105], v[96:97], v[126:127]
	v_pk_fma_f32 v[94:95], v[94:95], v[86:87], v[118:119]
	v_pk_fma_f32 v[92:93], v[92:93], v[84:85], v[128:129]
	v_pk_fma_f32 v[114:115], v[90:91], v[82:83], v[120:121]
	v_pk_fma_f32 v[116:117], v[88:89], v[80:81], v[130:131]
	v_cvt_pk_bf16_f32 v88, v108, v109
	v_cvt_pk_bf16_f32 v89, v110, v111
	v_cvt_pk_bf16_f32 v90, v104, v105
	v_mul_f32_e32 v91, v109, v109
	v_mul_f32_e32 v109, v111, v111
	v_mul_f32_e32 v105, v105, v105
	v_mul_f32_e32 v111, v107, v107
	v_mul_f32_e32 v118, v93, v93
	v_mul_f32_e32 v119, v95, v95
	v_mul_f32_e32 v120, v117, v117
	v_mul_f32_e32 v121, v115, v115
	v_fmac_f32_e32 v91, v108, v108
	v_fmac_f32_e32 v109, v110, v110
	v_fmac_f32_e32 v105, v104, v104
	v_fmac_f32_e32 v111, v106, v106
	v_fmac_f32_e32 v118, v92, v92
	v_fmac_f32_e32 v119, v94, v94
	v_fmac_f32_e32 v120, v116, v116
	v_fmac_f32_e32 v121, v114, v114
	v_add_f32_e32 v91, v91, v109
	v_add_f32_e32 v104, v105, v111
	v_add_f32_e32 v105, v118, v119
	v_add_f32_e32 v108, v120, v121
	v_add_f32_e32 v91, v91, v104
	v_add_f32_e32 v104, v105, v108
	v_add_f32_e32 v108, v91, v104
	ds_bpermute_b32 v109, v173, v108
	v_cvt_pk_bf16_f32 v91, v106, v107
	v_lshl_add_u64 v[104:105], s[24:25], 0, v[122:123]
	global_store_dwordx4 v[104:105], v[88:91], off
	s_waitcnt lgkmcnt(0)
	s_nop 0
	v_add_f32_e32 v88, v108, v109
	ds_bpermute_b32 v89, v172, v88
	v_cvt_pk_bf16_f32 v90, v92, v93
	v_cvt_pk_bf16_f32 v91, v94, v95
	v_cvt_pk_bf16_f32 v92, v116, v117
	v_cvt_pk_bf16_f32 v93, v114, v115
	global_store_dwordx4 v[104:105], v[90:93], off offset:256
	s_and_saveexec_b64 s[44:45], s[4:5]
	s_cbranch_execz .LBB0_817
	s_waitcnt lgkmcnt(0)
	v_add_f32_e32 v90, v88, v89
	v_lshlrev_b64 v[88:89], 6, v[112:113]
	v_lshl_add_u64 v[88:89], s[0:1], 0, v[88:89]
	v_lshl_add_u64 v[88:89], s[40:41], 2, v[88:89]
	s_lshl_b32 s12, s56, 2
	v_lshl_add_u64 v[88:89], v[88:89], 0, s[12:13]
	global_store_dword v[88:89], v90, off
;     __device__ __forceinline__ void operator()(const f32x4 (&acc)[2][2][4][2], const Unit& u, int wr, int wc, int fr, int fq) const {
;         const float* g = gate + (u.pm >> 5) * 9216;
;         const int row0 = u.pm * BM + wr * 64 + fr, col0 = u.pn * BM + wc * 32 + 8 * fq;
;         f32x4 gv[2][2];
; #pragma unroll
;         for (int bj = 0; bj < 2; ++bj)
; #pragma unroll
;             for (int n = 0; n < 2; ++n) gv[bj][n] = *(const f32x4*)(g + col0 + bj * HALF + 4 * n) * coef;
; #pragma unroll
;         for (int ai = 0; ai < 2; ++ai)
; #pragma unroll
;             for (int m = 0; m < 4; ++m) {
;                 const int row = row0 + ai * HALF + m * 16; const size_t off = (size_t)row * 1024 + col0;
;                 f32x4 b0[2], b1[2];
; #pragma unroll
;                 for (int bj = 0; bj < 2; ++bj) {
;                     if (BASE_BF16) { const u32x4 t = *(const u32x4*)((const bf16_t*)base + off + bj * HALF);
;                         b0[bj] = (f32x4){bf_lo(t.x), bf_hi(t.x), bf_lo(t.y), bf_hi(t.y)}; b1[bj] = (f32x4){bf_lo(t.z), bf_hi(t.z), bf_lo(t.w), bf_hi(t.w)}; }
;                     else { b0[bj] = *(const f32x4*)((const float*)base + off + bj * HALF); b1[bj] = *(const f32x4*)((const float*)base + off + bj * HALF + 4); }
;                 }
;                 float ss = 0.f;
; #pragma unroll
;                 for (int bj = 0; bj < 2; ++bj) {
;                     const f32x4 v0 = b0[bj] + gv[bj][0] * acc[ai][bj][m][0], v1 = b1[bj] + gv[bj][1] * acc[ai][bj][m][1];
;                     if (OUT_BF16) {
;                         u32x4 w; w.x = cvt_pk_bf16(v0[0], v0[1]); w.y = cvt_pk_bf16(v0[2], v0[3]); w.z = cvt_pk_bf16(v1[0], v1[1]); w.w = cvt_pk_bf16(v1[2], v1[3]);
;                         *(u32x4*)((bf16_t*)out + off + bj * HALF) = w;
;                         ss += ((v0[0] * v0[0] + v0[1] * v0[1]) + (v0[2] * v0[2] + v0[3] * v0[3])) + ((v1[0] * v1[0] + v1[1] * v1[1]) + (v1[2] * v1[2] + v1[3] * v1[3]));
;                     } else { *(f32x4*)((float*)out + off + bj * HALF) = v0; *(f32x4*)((float*)out + off + bj * HALF + 4) = v1; }
;                 }
;                 if (OUT_BF16) { ss += __shfl_xor(ss, 16); ss += __shfl_xor(ss, 32); if (fq == 0) rowp[(size_t)row * 16 + u.pn * 4 + wc] = ss; }
;             }
.LBB0_817:
	s_or_b64 exec, exec, s[44:45]
	v_or_b32_e32 v88, 48, v164
	s_waitcnt lgkmcnt(0)
	v_ashrrev_i32_e32 v89, 31, v88
	v_lshlrev_b64 v[90:91], 10, v[88:89]
	v_lshl_add_u64 v[90:91], v[90:91], 0, v[160:161]
	v_lshlrev_b64 v[94:95], 1, v[90:91]
	v_lshl_add_u64 v[104:105], s[84:85], 0, v[94:95]
	s_waitcnt vmcnt(14)
	v_mov_b32_e32 v90, v208
	v_mov_b32_e32 v91, v209
	v_mov_b32_e32 v92, v210
	v_mov_b32_e32 v93, v211
	v_mov_b32_e32 v104, v212
	v_mov_b32_e32 v105, v213
	v_mov_b32_e32 v106, v214
	v_mov_b32_e32 v107, v215
	v_lshlrev_b32_e32 v108, 16, v90
	v_and_b32_e32 v109, 0xffff0000, v90
	v_lshlrev_b32_e32 v90, 16, v91
	v_and_b32_e32 v91, 0xffff0000, v91
	v_lshlrev_b32_e32 v110, 16, v92
	v_and_b32_e32 v111, 0xffff0000, v92
	v_lshlrev_b32_e32 v92, 16, v93
	v_and_b32_e32 v93, 0xffff0000, v93
	v_lshlrev_b32_e32 v112, 16, v104
	v_and_b32_e32 v113, 0xffff0000, v104
	v_lshlrev_b32_e32 v104, 16, v105
	v_and_b32_e32 v105, 0xffff0000, v105
	v_lshlrev_b32_e32 v114, 16, v106
	v_and_b32_e32 v115, 0xffff0000, v106
	v_lshlrev_b32_e32 v106, 16, v107
	v_and_b32_e32 v107, 0xffff0000, v107
	v_pk_fma_f32 v[78:79], v[78:79], v[102:103], v[90:91]
	v_pk_fma_f32 v[76:77], v[76:77], v[100:101], v[108:109]
	v_pk_fma_f32 v[74:75], v[74:75], v[98:99], v[92:93]
	v_pk_fma_f32 v[72:73], v[72:73], v[96:97], v[110:111]
	v_pk_fma_f32 v[70:71], v[70:71], v[86:87], v[104:105]
	v_pk_fma_f32 v[68:69], v[68:69], v[84:85], v[112:113]
	v_pk_fma_f32 v[90:91], v[66:67], v[82:83], v[106:107]
	v_pk_fma_f32 v[92:93], v[64:65], v[80:81], v[114:115]
	v_cvt_pk_bf16_f32 v64, v76, v77
	v_cvt_pk_bf16_f32 v65, v78, v79
	v_cvt_pk_bf16_f32 v66, v72, v73
	v_mul_f32_e32 v67, v77, v77
	v_mul_f32_e32 v77, v79, v79
	v_mul_f32_e32 v73, v73, v73
	v_mul_f32_e32 v79, v75, v75
	v_mul_f32_e32 v104, v69, v69
	v_mul_f32_e32 v105, v71, v71
	v_mul_f32_e32 v106, v93, v93
	v_mul_f32_e32 v107, v91, v91
	v_fmac_f32_e32 v67, v76, v76
	v_fmac_f32_e32 v77, v78, v78
	v_fmac_f32_e32 v73, v72, v72
	v_fmac_f32_e32 v79, v74, v74
	v_fmac_f32_e32 v104, v68, v68
	v_fmac_f32_e32 v105, v70, v70
	v_fmac_f32_e32 v106, v92, v92
	v_fmac_f32_e32 v107, v90, v90
	v_add_f32_e32 v67, v67, v77
	v_add_f32_e32 v72, v73, v79
	v_add_f32_e32 v73, v104, v105
	v_add_f32_e32 v76, v106, v107
	v_add_f32_e32 v67, v67, v72
	v_add_f32_e32 v72, v73, v76
	v_add_f32_e32 v76, v67, v72
	ds_bpermute_b32 v77, v173, v76
	v_cvt_pk_bf16_f32 v67, v74, v75
	v_lshl_add_u64 v[72:73], s[24:25], 0, v[94:95]
	global_store_dwordx4 v[72:73], v[64:67], off
	s_waitcnt lgkmcnt(0)
	s_nop 0
	v_add_f32_e32 v64, v76, v77
	ds_bpermute_b32 v65, v172, v64
	v_cvt_pk_bf16_f32 v66, v68, v69
	v_cvt_pk_bf16_f32 v67, v70, v71
	v_cvt_pk_bf16_f32 v68, v92, v93
	v_cvt_pk_bf16_f32 v69, v90, v91
	global_store_dwordx4 v[72:73], v[66:69], off offset:256
	s_and_saveexec_b64 s[44:45], s[4:5]
	s_cbranch_execz .LBB0_819
	s_waitcnt lgkmcnt(0)
	v_add_f32_e32 v66, v64, v65
	v_lshlrev_b64 v[64:65], 6, v[88:89]
	v_lshl_add_u64 v[64:65], s[0:1], 0, v[64:65]
	v_lshl_add_u64 v[64:65], s[40:41], 2, v[64:65]
	s_lshl_b32 s12, s56, 2
	v_lshl_add_u64 v[64:65], v[64:65], 0, s[12:13]
	global_store_dword v[64:65], v66, off
.LBB0_819:
	s_or_b64 exec, exec, s[44:45]
	v_add_u32_e32 v64, 0x80, v164
	s_waitcnt lgkmcnt(0)
	v_ashrrev_i32_e32 v65, 31, v64
	v_lshlrev_b64 v[66:67], 10, v[64:65]
	v_lshl_add_u64 v[66:67], v[66:67], 0, v[160:161]
	v_lshlrev_b64 v[74:75], 1, v[66:67]
	v_lshl_add_u64 v[70:71], s[84:85], 0, v[74:75]
	s_waitcnt vmcnt(14)
	v_mov_b32_e32 v66, v216
	v_mov_b32_e32 v67, v217
	v_mov_b32_e32 v68, v218
	v_mov_b32_e32 v69, v219
	v_mov_b32_e32 v70, v220
	v_mov_b32_e32 v71, v221
	v_mov_b32_e32 v72, v222
	v_mov_b32_e32 v73, v223
	v_lshlrev_b32_e32 v76, 16, v66
	v_and_b32_e32 v77, 0xffff0000, v66
	v_lshlrev_b32_e32 v66, 16, v67
	v_and_b32_e32 v67, 0xffff0000, v67
	v_lshlrev_b32_e32 v78, 16, v68
	v_and_b32_e32 v79, 0xffff0000, v68
	v_lshlrev_b32_e32 v68, 16, v69
	v_and_b32_e32 v69, 0xffff0000, v69
	v_lshlrev_b32_e32 v88, 16, v70
	v_and_b32_e32 v89, 0xffff0000, v70
	v_lshlrev_b32_e32 v70, 16, v71
	v_and_b32_e32 v71, 0xffff0000, v71
	v_lshlrev_b32_e32 v90, 16, v72
	v_and_b32_e32 v91, 0xffff0000, v72
	v_lshlrev_b32_e32 v72, 16, v73
	v_and_b32_e32 v73, 0xffff0000, v73
	v_pk_fma_f32 v[62:63], v[62:63], v[102:103], v[66:67]
	v_pk_fma_f32 v[60:61], v[60:61], v[100:101], v[76:77]
	v_pk_fma_f32 v[58:59], v[58:59], v[98:99], v[68:69]
	v_pk_fma_f32 v[56:57], v[56:57], v[96:97], v[78:79]
	v_pk_fma_f32 v[54:55], v[54:55], v[86:87], v[70:71]
	v_pk_fma_f32 v[52:53], v[52:53], v[84:85], v[88:89]
	v_pk_fma_f32 v[66:67], v[50:51], v[82:83], v[72:73]
	v_pk_fma_f32 v[68:69], v[48:49], v[80:81], v[90:91]
	v_cvt_pk_bf16_f32 v48, v60, v61
	v_cvt_pk_bf16_f32 v49, v62, v63
	v_cvt_pk_bf16_f32 v50, v56, v57
	v_mul_f32_e32 v51, v61, v61
	v_mul_f32_e32 v61, v63, v63
	v_mul_f32_e32 v57, v57, v57
	v_mul_f32_e32 v63, v59, v59
	v_mul_f32_e32 v70, v53, v53
	v_mul_f32_e32 v71, v55, v55
	v_mul_f32_e32 v72, v69, v69
	v_mul_f32_e32 v73, v67, v67
	v_fmac_f32_e32 v51, v60, v60
	v_fmac_f32_e32 v61, v62, v62
	v_fmac_f32_e32 v57, v56, v56
	v_fmac_f32_e32 v63, v58, v58
	v_fmac_f32_e32 v70, v52, v52
	v_fmac_f32_e32 v71, v54, v54
	v_fmac_f32_e32 v72, v68, v68
	v_fmac_f32_e32 v73, v66, v66
	v_add_f32_e32 v51, v51, v61
	v_add_f32_e32 v56, v57, v63
	v_add_f32_e32 v57, v70, v71
	v_add_f32_e32 v60, v72, v73
	v_add_f32_e32 v51, v51, v56
	v_add_f32_e32 v56, v57, v60
	v_add_f32_e32 v60, v51, v56
	ds_bpermute_b32 v61, v173, v60
	v_cvt_pk_bf16_f32 v51, v58, v59
	v_lshl_add_u64 v[56:57], s[24:25], 0, v[74:75]
	global_store_dwordx4 v[56:57], v[48:51], off
	s_waitcnt lgkmcnt(0)
	s_nop 0
	v_add_f32_e32 v48, v60, v61
	ds_bpermute_b32 v49, v172, v48
	v_cvt_pk_bf16_f32 v50, v52, v53
	v_cvt_pk_bf16_f32 v51, v54, v55
	v_cvt_pk_bf16_f32 v52, v68, v69
	v_cvt_pk_bf16_f32 v53, v66, v67
	global_store_dwordx4 v[56:57], v[50:53], off offset:256
	s_and_saveexec_b64 s[44:45], s[4:5]
	s_cbranch_execz .LBB0_821
	s_waitcnt lgkmcnt(0)
	v_add_f32_e32 v50, v48, v49
	v_lshlrev_b64 v[48:49], 6, v[64:65]
	v_lshl_add_u64 v[48:49], s[0:1], 0, v[48:49]
	v_lshl_add_u64 v[48:49], s[40:41], 2, v[48:49]
	s_lshl_b32 s12, s56, 2
	v_lshl_add_u64 v[48:49], v[48:49], 0, s[12:13]
	global_store_dword v[48:49], v50, off
;     __device__ __forceinline__ void operator()(const f32x4 (&acc)[2][2][4][2], const Unit& u, int wr, int wc, int fr, int fq) const {
;         const float* g = gate + (u.pm >> 5) * 9216;
;         const int row0 = u.pm * BM + wr * 64 + fr, col0 = u.pn * BM + wc * 32 + 8 * fq;
;         f32x4 gv[2][2];
; #pragma unroll
;         for (int bj = 0; bj < 2; ++bj)
; #pragma unroll
;             for (int n = 0; n < 2; ++n) gv[bj][n] = *(const f32x4*)(g + col0 + bj * HALF + 4 * n) * coef;
; #pragma unroll
;         for (int ai = 0; ai < 2; ++ai)
; #pragma unroll
;             for (int m = 0; m < 4; ++m) {
;                 const int row = row0 + ai * HALF + m * 16; const size_t off = (size_t)row * 1024 + col0;
;                 f32x4 b0[2], b1[2];
; #pragma unroll
;                 for (int bj = 0; bj < 2; ++bj) {
;                     if (BASE_BF16) { const u32x4 t = *(const u32x4*)((const bf16_t*)base + off + bj * HALF);
;                         b0[bj] = (f32x4){bf_lo(t.x), bf_hi(t.x), bf_lo(t.y), bf_hi(t.y)}; b1[bj] = (f32x4){bf_lo(t.z), bf_hi(t.z), bf_lo(t.w), bf_hi(t.w)}; }
;                     else { b0[bj] = *(const f32x4*)((const float*)base + off + bj * HALF); b1[bj] = *(const f32x4*)((const float*)base + off + bj * HALF + 4); }
;                 }
;                 float ss = 0.f;
; #pragma unroll
;                 for (int bj = 0; bj < 2; ++bj) {
;                     const f32x4 v0 = b0[bj] + gv[bj][0] * acc[ai][bj][m][0], v1 = b1[bj] + gv[bj][1] * acc[ai][bj][m][1];
;                     if (OUT_BF16) {
;                         u32x4 w; w.x = cvt_pk_bf16(v0[0], v0[1]); w.y = cvt_pk_bf16(v0[2], v0[3]); w.z = cvt_pk_bf16(v1[0], v1[1]); w.w = cvt_pk_bf16(v1[2], v1[3]);
;                         *(u32x4*)((bf16_t*)out + off + bj * HALF) = w;
;                         ss += ((v0[0] * v0[0] + v0[1] * v0[1]) + (v0[2] * v0[2] + v0[3] * v0[3])) + ((v1[0] * v1[0] + v1[1] * v1[1]) + (v1[2] * v1[2] + v1[3] * v1[3]));
;                     } else { *(f32x4*)((float*)out + off + bj * HALF) = v0; *(f32x4*)((float*)out + off + bj * HALF + 4) = v1; }
;                 }
;                 if (OUT_BF16) { ss += __shfl_xor(ss, 16); ss += __shfl_xor(ss, 32); if (fq == 0) rowp[(size_t)row * 16 + u.pn * 4 + wc] = ss; }
;             }
.LBB0_821:
	s_or_b64 exec, exec, s[44:45]
	v_add_u32_e32 v48, 0x90, v164
	s_waitcnt lgkmcnt(0)
	v_ashrrev_i32_e32 v49, 31, v48
	v_lshlrev_b64 v[50:51], 10, v[48:49]
	v_lshl_add_u64 v[50:51], v[50:51], 0, v[160:161]
	v_lshlrev_b64 v[58:59], 1, v[50:51]
	v_lshl_add_u64 v[54:55], s[84:85], 0, v[58:59]
	s_waitcnt vmcnt(14)
	v_mov_b32_e32 v50, v228
	v_mov_b32_e32 v51, v229
	v_mov_b32_e32 v52, v230
	v_mov_b32_e32 v53, v231
	v_mov_b32_e32 v54, v232
	v_mov_b32_e32 v55, v233
	v_mov_b32_e32 v56, v234
	v_mov_b32_e32 v57, v235
	v_lshlrev_b32_e32 v60, 16, v50
	v_and_b32_e32 v61, 0xffff0000, v50
	v_lshlrev_b32_e32 v50, 16, v51
	v_and_b32_e32 v51, 0xffff0000, v51
	v_lshlrev_b32_e32 v62, 16, v52
	v_and_b32_e32 v63, 0xffff0000, v52
	v_lshlrev_b32_e32 v52, 16, v53
	v_and_b32_e32 v53, 0xffff0000, v53
	v_lshlrev_b32_e32 v64, 16, v54
	v_and_b32_e32 v65, 0xffff0000, v54
	v_lshlrev_b32_e32 v54, 16, v55
	v_and_b32_e32 v55, 0xffff0000, v55
	v_lshlrev_b32_e32 v66, 16, v56
	v_and_b32_e32 v67, 0xffff0000, v56
	v_lshlrev_b32_e32 v56, 16, v57
	v_and_b32_e32 v57, 0xffff0000, v57
	v_pk_fma_f32 v[46:47], v[46:47], v[102:103], v[50:51]
	v_pk_fma_f32 v[44:45], v[44:45], v[100:101], v[60:61]
	v_pk_fma_f32 v[42:43], v[42:43], v[98:99], v[52:53]
	v_pk_fma_f32 v[40:41], v[40:41], v[96:97], v[62:63]
	v_pk_fma_f32 v[38:39], v[38:39], v[86:87], v[54:55]
	v_pk_fma_f32 v[36:37], v[36:37], v[84:85], v[64:65]
	v_pk_fma_f32 v[50:51], v[34:35], v[82:83], v[56:57]
	v_pk_fma_f32 v[52:53], v[32:33], v[80:81], v[66:67]
	v_cvt_pk_bf16_f32 v32, v44, v45
	v_cvt_pk_bf16_f32 v33, v46, v47
	v_cvt_pk_bf16_f32 v34, v40, v41
	v_mul_f32_e32 v35, v45, v45
	v_mul_f32_e32 v45, v47, v47
	v_mul_f32_e32 v41, v41, v41
	v_mul_f32_e32 v47, v43, v43
	v_mul_f32_e32 v54, v37, v37
	v_mul_f32_e32 v55, v39, v39
	v_mul_f32_e32 v56, v53, v53
	v_mul_f32_e32 v57, v51, v51
	v_fmac_f32_e32 v35, v44, v44
	v_fmac_f32_e32 v45, v46, v46
	v_fmac_f32_e32 v41, v40, v40
	v_fmac_f32_e32 v47, v42, v42
	v_fmac_f32_e32 v54, v36, v36
	v_fmac_f32_e32 v55, v38, v38
	v_fmac_f32_e32 v56, v52, v52
	v_fmac_f32_e32 v57, v50, v50
	v_add_f32_e32 v35, v35, v45
	v_add_f32_e32 v40, v41, v47
	v_add_f32_e32 v41, v54, v55
	v_add_f32_e32 v44, v56, v57
	v_add_f32_e32 v35, v35, v40
	v_add_f32_e32 v40, v41, v44
	v_add_f32_e32 v44, v35, v40
	ds_bpermute_b32 v45, v173, v44
	v_cvt_pk_bf16_f32 v35, v42, v43
	v_lshl_add_u64 v[40:41], s[24:25], 0, v[58:59]
	global_store_dwordx4 v[40:41], v[32:35], off
	s_waitcnt lgkmcnt(0)
	s_nop 0
	v_add_f32_e32 v32, v44, v45
	ds_bpermute_b32 v33, v172, v32
	v_cvt_pk_bf16_f32 v34, v36, v37
	v_cvt_pk_bf16_f32 v35, v38, v39
	v_cvt_pk_bf16_f32 v36, v52, v53
	v_cvt_pk_bf16_f32 v37, v50, v51
	global_store_dwordx4 v[40:41], v[34:37], off offset:256
	s_and_saveexec_b64 s[44:45], s[4:5]
	s_cbranch_execz .LBB0_823
	s_waitcnt lgkmcnt(0)
	v_add_f32_e32 v34, v32, v33
	v_lshlrev_b64 v[32:33], 6, v[48:49]
	v_lshl_add_u64 v[32:33], s[0:1], 0, v[32:33]
	v_lshl_add_u64 v[32:33], s[40:41], 2, v[32:33]
	s_lshl_b32 s12, s56, 2
	v_lshl_add_u64 v[32:33], v[32:33], 0, s[12:13]
	global_store_dword v[32:33], v34, off
;     __device__ __forceinline__ void operator()(const f32x4 (&acc)[2][2][4][2], const Unit& u, int wr, int wc, int fr, int fq) const {
;         const float* g = gate + (u.pm >> 5) * 9216;
;         const int row0 = u.pm * BM + wr * 64 + fr, col0 = u.pn * BM + wc * 32 + 8 * fq;
;         f32x4 gv[2][2];
; #pragma unroll
;         for (int bj = 0; bj < 2; ++bj)
; #pragma unroll
;             for (int n = 0; n < 2; ++n) gv[bj][n] = *(const f32x4*)(g + col0 + bj * HALF + 4 * n) * coef;
; #pragma unroll
;         for (int ai = 0; ai < 2; ++ai)
; #pragma unroll
;             for (int m = 0; m < 4; ++m) {
;                 const int row = row0 + ai * HALF + m * 16; const size_t off = (size_t)row * 1024 + col0;
;                 f32x4 b0[2], b1[2];
; #pragma unroll
;                 for (int bj = 0; bj < 2; ++bj) {
;                     if (BASE_BF16) { const u32x4 t = *(const u32x4*)((const bf16_t*)base + off + bj * HALF);
;                         b0[bj] = (f32x4){bf_lo(t.x), bf_hi(t.x), bf_lo(t.y), bf_hi(t.y)}; b1[bj] = (f32x4){bf_lo(t.z), bf_hi(t.z), bf_lo(t.w), bf_hi(t.w)}; }
;                     else { b0[bj] = *(const f32x4*)((const float*)base + off + bj * HALF); b1[bj] = *(const f32x4*)((const float*)base + off + bj * HALF + 4); }
;                 }
;                 float ss = 0.f;
; #pragma unroll
;                 for (int bj = 0; bj < 2; ++bj) {
;                     const f32x4 v0 = b0[bj] + gv[bj][0] * acc[ai][bj][m][0], v1 = b1[bj] + gv[bj][1] * acc[ai][bj][m][1];
;                     if (OUT_BF16) {
;                         u32x4 w; w.x = cvt_pk_bf16(v0[0], v0[1]); w.y = cvt_pk_bf16(v0[2], v0[3]); w.z = cvt_pk_bf16(v1[0], v1[1]); w.w = cvt_pk_bf16(v1[2], v1[3]);
;                         *(u32x4*)((bf16_t*)out + off + bj * HALF) = w;
;                         ss += ((v0[0] * v0[0] + v0[1] * v0[1]) + (v0[2] * v0[2] + v0[3] * v0[3])) + ((v1[0] * v1[0] + v1[1] * v1[1]) + (v1[2] * v1[2] + v1[3] * v1[3]));
;                     } else { *(f32x4*)((float*)out + off + bj * HALF) = v0; *(f32x4*)((float*)out + off + bj * HALF + 4) = v1; }
;                 }
;                 if (OUT_BF16) { ss += __shfl_xor(ss, 16); ss += __shfl_xor(ss, 32); if (fq == 0) rowp[(size_t)row * 16 + u.pn * 4 + wc] = ss; }
;             }
.LBB0_823:
	s_or_b64 exec, exec, s[44:45]
	v_add_u32_e32 v32, 0xa0, v164
	s_waitcnt lgkmcnt(0)
	v_ashrrev_i32_e32 v33, 31, v32
	v_lshlrev_b64 v[34:35], 10, v[32:33]
	v_lshl_add_u64 v[34:35], v[34:35], 0, v[160:161]
	v_lshlrev_b64 v[42:43], 1, v[34:35]
	v_lshl_add_u64 v[38:39], s[84:85], 0, v[42:43]
	s_waitcnt vmcnt(14)
	v_mov_b32_e32 v34, v236
	v_mov_b32_e32 v35, v237
	v_mov_b32_e32 v36, v238
	v_mov_b32_e32 v37, v239
	v_mov_b32_e32 v38, v240
	v_mov_b32_e32 v39, v241
	v_mov_b32_e32 v40, v242
	v_mov_b32_e32 v41, v243
	v_lshlrev_b32_e32 v44, 16, v34
	v_and_b32_e32 v45, 0xffff0000, v34
	v_lshlrev_b32_e32 v34, 16, v35
	v_and_b32_e32 v35, 0xffff0000, v35
	v_lshlrev_b32_e32 v46, 16, v36
	v_and_b32_e32 v47, 0xffff0000, v36
	v_lshlrev_b32_e32 v36, 16, v37
	v_and_b32_e32 v37, 0xffff0000, v37
	v_lshlrev_b32_e32 v48, 16, v38
	v_and_b32_e32 v49, 0xffff0000, v38
	v_lshlrev_b32_e32 v38, 16, v39
	v_and_b32_e32 v39, 0xffff0000, v39
	v_lshlrev_b32_e32 v50, 16, v40
	v_and_b32_e32 v51, 0xffff0000, v40
	v_lshlrev_b32_e32 v40, 16, v41
	v_and_b32_e32 v41, 0xffff0000, v41
	v_pk_fma_f32 v[30:31], v[30:31], v[102:103], v[34:35]
	v_pk_fma_f32 v[28:29], v[28:29], v[100:101], v[44:45]
	v_pk_fma_f32 v[26:27], v[26:27], v[98:99], v[36:37]
	v_pk_fma_f32 v[24:25], v[24:25], v[96:97], v[46:47]
	v_pk_fma_f32 v[22:23], v[22:23], v[86:87], v[38:39]
	v_pk_fma_f32 v[20:21], v[20:21], v[84:85], v[48:49]
	v_pk_fma_f32 v[34:35], v[18:19], v[82:83], v[40:41]
	v_pk_fma_f32 v[36:37], v[16:17], v[80:81], v[50:51]
	v_cvt_pk_bf16_f32 v16, v28, v29
	v_cvt_pk_bf16_f32 v17, v30, v31
	v_cvt_pk_bf16_f32 v18, v24, v25
	v_mul_f32_e32 v19, v29, v29
	v_mul_f32_e32 v29, v31, v31
	v_mul_f32_e32 v25, v25, v25
	v_mul_f32_e32 v31, v27, v27
	v_mul_f32_e32 v38, v21, v21
	v_mul_f32_e32 v39, v23, v23
	v_mul_f32_e32 v40, v37, v37
	v_mul_f32_e32 v41, v35, v35
	v_fmac_f32_e32 v19, v28, v28
	v_fmac_f32_e32 v29, v30, v30
	v_fmac_f32_e32 v25, v24, v24
	v_fmac_f32_e32 v31, v26, v26
	v_fmac_f32_e32 v38, v20, v20
	v_fmac_f32_e32 v39, v22, v22
	v_fmac_f32_e32 v40, v36, v36
	v_fmac_f32_e32 v41, v34, v34
	v_add_f32_e32 v19, v19, v29
	v_add_f32_e32 v24, v25, v31
	v_add_f32_e32 v25, v38, v39
	v_add_f32_e32 v28, v40, v41
	v_add_f32_e32 v19, v19, v24
	v_add_f32_e32 v24, v25, v28
	v_add_f32_e32 v28, v19, v24
	ds_bpermute_b32 v29, v173, v28
	v_cvt_pk_bf16_f32 v19, v26, v27
	v_lshl_add_u64 v[24:25], s[24:25], 0, v[42:43]
	global_store_dwordx4 v[24:25], v[16:19], off
	s_waitcnt lgkmcnt(0)
	s_nop 0
	v_add_f32_e32 v16, v28, v29
	ds_bpermute_b32 v17, v172, v16
	v_cvt_pk_bf16_f32 v18, v20, v21
	v_cvt_pk_bf16_f32 v19, v22, v23
	v_cvt_pk_bf16_f32 v20, v36, v37
	v_cvt_pk_bf16_f32 v21, v34, v35
	global_store_dwordx4 v[24:25], v[18:21], off offset:256
	s_and_saveexec_b64 s[44:45], s[4:5]
	s_cbranch_execz .LBB0_825
	s_waitcnt lgkmcnt(0)
	v_add_f32_e32 v18, v16, v17
	v_lshlrev_b64 v[16:17], 6, v[32:33]
	v_lshl_add_u64 v[16:17], s[0:1], 0, v[16:17]
	v_lshl_add_u64 v[16:17], s[40:41], 2, v[16:17]
	s_lshl_b32 s12, s56, 2
	v_lshl_add_u64 v[16:17], v[16:17], 0, s[12:13]
	global_store_dword v[16:17], v18, off
.LBB0_825:
	s_or_b64 exec, exec, s[44:45]
	v_add_u32_e32 v16, 0xb0, v164
	s_waitcnt lgkmcnt(0)
	v_ashrrev_i32_e32 v17, 31, v16
	v_lshlrev_b64 v[18:19], 10, v[16:17]
	v_lshl_add_u64 v[18:19], v[18:19], 0, v[160:161]
	v_lshlrev_b64 v[26:27], 1, v[18:19]
	v_lshl_add_u64 v[22:23], s[84:85], 0, v[26:27]
	s_waitcnt vmcnt(14)
	v_mov_b32_e32 v18, v244
	v_mov_b32_e32 v19, v245
	v_mov_b32_e32 v20, v246
	v_mov_b32_e32 v21, v247
	v_mov_b32_e32 v22, v248
	v_mov_b32_e32 v23, v249
	v_mov_b32_e32 v24, v250
	v_mov_b32_e32 v25, v251
	v_lshlrev_b32_e32 v28, 16, v18
	v_and_b32_e32 v29, 0xffff0000, v18
	v_lshlrev_b32_e32 v18, 16, v19
	v_and_b32_e32 v19, 0xffff0000, v19
	v_lshlrev_b32_e32 v30, 16, v20
	v_and_b32_e32 v31, 0xffff0000, v20
	v_lshlrev_b32_e32 v20, 16, v21
	v_and_b32_e32 v21, 0xffff0000, v21
	v_lshlrev_b32_e32 v32, 16, v22
	v_and_b32_e32 v33, 0xffff0000, v22
	v_lshlrev_b32_e32 v22, 16, v23
	v_and_b32_e32 v23, 0xffff0000, v23
	v_lshlrev_b32_e32 v34, 16, v24
	v_and_b32_e32 v35, 0xffff0000, v24
	v_lshlrev_b32_e32 v24, 16, v25
	v_and_b32_e32 v25, 0xffff0000, v25
	v_pk_fma_f32 v[14:15], v[14:15], v[102:103], v[18:19]
	v_pk_fma_f32 v[12:13], v[12:13], v[100:101], v[28:29]
	v_pk_fma_f32 v[10:11], v[10:11], v[98:99], v[20:21]
	v_pk_fma_f32 v[8:9], v[8:9], v[96:97], v[30:31]
	v_pk_fma_f32 v[6:7], v[6:7], v[86:87], v[22:23]
	v_pk_fma_f32 v[4:5], v[4:5], v[84:85], v[32:33]
	v_pk_fma_f32 v[18:19], v[2:3], v[82:83], v[24:25]
	v_pk_fma_f32 v[20:21], v[0:1], v[80:81], v[34:35]
	v_cvt_pk_bf16_f32 v0, v12, v13
	v_cvt_pk_bf16_f32 v1, v14, v15
	v_cvt_pk_bf16_f32 v2, v8, v9
	v_mul_f32_e32 v3, v13, v13
	v_mul_f32_e32 v13, v15, v15
	v_mul_f32_e32 v9, v9, v9
	v_mul_f32_e32 v15, v11, v11
	v_mul_f32_e32 v22, v5, v5
	v_mul_f32_e32 v23, v7, v7
	v_mul_f32_e32 v24, v21, v21
	v_mul_f32_e32 v25, v19, v19
	v_fmac_f32_e32 v3, v12, v12
	v_fmac_f32_e32 v13, v14, v14
	v_fmac_f32_e32 v9, v8, v8
	v_fmac_f32_e32 v15, v10, v10
	v_fmac_f32_e32 v22, v4, v4
	v_fmac_f32_e32 v23, v6, v6
	v_fmac_f32_e32 v24, v20, v20
	v_fmac_f32_e32 v25, v18, v18
	v_add_f32_e32 v3, v3, v13
	v_add_f32_e32 v8, v9, v15
	v_add_f32_e32 v9, v22, v23
	v_add_f32_e32 v12, v24, v25
	v_add_f32_e32 v3, v3, v8
	v_add_f32_e32 v8, v9, v12
	v_add_f32_e32 v12, v3, v8
	ds_bpermute_b32 v13, v173, v12
	v_cvt_pk_bf16_f32 v3, v10, v11
	v_lshl_add_u64 v[8:9], s[24:25], 0, v[26:27]
	global_store_dwordx4 v[8:9], v[0:3], off
	s_waitcnt lgkmcnt(0)
	s_nop 0
	v_add_f32_e32 v0, v12, v13
	ds_bpermute_b32 v1, v172, v0
	v_cvt_pk_bf16_f32 v2, v4, v5
	v_cvt_pk_bf16_f32 v3, v6, v7
	v_cvt_pk_bf16_f32 v4, v20, v21
	v_cvt_pk_bf16_f32 v5, v18, v19
	global_store_dwordx4 v[8:9], v[2:5], off offset:256
	s_and_saveexec_b64 s[44:45], s[4:5]
	s_cbranch_execz .LBB0_827
	s_waitcnt lgkmcnt(0)
	v_add_f32_e32 v2, v0, v1
	v_lshlrev_b64 v[0:1], 6, v[16:17]
	v_lshl_add_u64 v[0:1], s[0:1], 0, v[0:1]
	v_lshl_add_u64 v[0:1], s[40:41], 2, v[0:1]
	s_lshl_b32 s12, s56, 2
	v_lshl_add_u64 v[0:1], v[0:1], 0, s[12:13]
	global_store_dword v[0:1], v2, off

; template <class Epi, class Sched, bool ALIGN_EPI = false, bool SP2 = false>
; __device__ __forceinline__ void gemm_phase(PG8_LAS unsigned char* lds, const Gemm g, const Sched& S, const Epi& E) {
;     ...
;         for (int a = 0; a < 2; ++a)
; #pragma unroll
;             for (int b = 0; b < 2; ++b)
; #pragma unroll
;                 for (int m = 0; m < 4; ++m)
; #pragma unroll
;                     for (int n = 0; n < 2; ++n) acc[a][b][m][n] = (f32x4){0.f, 0.f, 0.f, 0.f};
.LBB0_906:
	s_ashr_i32 s23, s22, 31
	s_lshl_b64 s[28:29], s[22:23], 19
	s_add_u32 s28, s24, s28
	s_addc_u32 s29, s25, s29
	s_and_b64 s[38:39], s[4:5], exec
	s_cselect_b32 s23, s29, s37
	s_cselect_b32 s58, s28, s36
	s_ashr_i32 s21, s20, 31
	s_lshl_b64 s[38:39], s[20:21], 19
	v_lshl_add_u64 v[162:163], v[144:145], 0, s[38:39]
	v_cndmask_b32_e64 v128, v0, v162, s[4:5]
	s_add_u32 s36, s36, 0x40080
	v_lshl_add_u64 v[130:131], v[0:1], 0, s[18:19]
	v_mov_b32_e32 v0, 0
	v_cndmask_b32_e64 v129, v1, v163, s[4:5]
	s_addc_u32 s37, s37, 0
	s_mov_b32 s21, -2
	v_mov_b32_e32 v1, v0
	v_mov_b64_e32 v[2:3], 0
	v_mov_b64_e32 v[4:5], 0
	v_mov_b64_e32 v[6:7], 0
	v_mov_b64_e32 v[16:17], 0
	v_mov_b64_e32 v[18:19], 0
	v_mov_b64_e32 v[20:21], 0
	v_mov_b64_e32 v[22:23], 0
	v_mov_b64_e32 v[32:33], 0
	v_mov_b64_e32 v[34:35], 0
	v_mov_b64_e32 v[36:37], 0
	v_mov_b64_e32 v[38:39], 0
	v_mov_b64_e32 v[48:49], 0
	v_mov_b64_e32 v[50:51], 0
	v_mov_b64_e32 v[52:53], 0
	v_mov_b64_e32 v[54:55], 0
	v_mov_b64_e32 v[8:9], 0
	v_mov_b64_e32 v[10:11], 0
	v_mov_b64_e32 v[12:13], 0
	v_mov_b64_e32 v[14:15], 0
	v_mov_b64_e32 v[24:25], 0
	v_mov_b64_e32 v[26:27], 0
	v_mov_b64_e32 v[28:29], 0
	v_mov_b64_e32 v[30:31], 0
	v_mov_b64_e32 v[40:41], 0
	v_mov_b64_e32 v[42:43], 0
	v_mov_b64_e32 v[44:45], 0
	v_mov_b64_e32 v[46:47], 0
	v_mov_b64_e32 v[56:57], 0
	v_mov_b64_e32 v[58:59], 0
	v_mov_b64_e32 v[60:61], 0
	v_mov_b64_e32 v[62:63], 0
	v_mov_b64_e32 v[64:65], 0
	v_mov_b64_e32 v[66:67], 0
	v_mov_b64_e32 v[68:69], 0
	v_mov_b64_e32 v[70:71], 0
	v_mov_b64_e32 v[80:81], 0
	v_mov_b64_e32 v[82:83], 0
	v_mov_b64_e32 v[84:85], 0
	v_mov_b64_e32 v[86:87], 0
	v_mov_b64_e32 v[96:97], 0
	v_mov_b64_e32 v[98:99], 0
	v_mov_b64_e32 v[100:101], 0
	v_mov_b64_e32 v[102:103], 0
	v_mov_b64_e32 v[112:113], 0
	v_mov_b64_e32 v[114:115], 0
	v_mov_b64_e32 v[116:117], 0
	v_mov_b64_e32 v[118:119], 0
	v_mov_b64_e32 v[72:73], 0
	v_mov_b64_e32 v[74:75], 0
	v_mov_b64_e32 v[76:77], 0
	v_mov_b64_e32 v[78:79], 0
	v_mov_b64_e32 v[88:89], 0
	v_mov_b64_e32 v[90:91], 0
	v_mov_b64_e32 v[92:93], 0
	v_mov_b64_e32 v[94:95], 0
	v_mov_b64_e32 v[104:105], 0
	v_mov_b64_e32 v[106:107], 0
	v_mov_b64_e32 v[108:109], 0
	v_mov_b64_e32 v[110:111], 0
	v_mov_b64_e32 v[120:121], 0
	v_mov_b64_e32 v[122:123], 0
	v_mov_b64_e32 v[124:125], 0
	v_mov_b64_e32 v[126:127], 0

; template <class Epi, class Sched, bool ALIGN_EPI = false, bool SP2 = false>
; __device__ __forceinline__ void gemm_phase(PG8_LAS unsigned char* lds, const Gemm g, const Sched& S, const Epi& E) {
;     ...
;         for (int a = 0; a < 2; ++a)
; #pragma unroll
;             for (int b = 0; b < 2; ++b)
; #pragma unroll
;                 for (int m = 0; m < 4; ++m)
; #pragma unroll
;                     for (int n = 0; n < 2; ++n) acc[a][b][m][n] = (f32x4){0.f, 0.f, 0.f, 0.f};
.LBB0_1006:
	s_add_u32 s22, s22, 0xb0080
	s_addc_u32 s23, s23, 0
	s_add_u32 s51, s26, 0x100
	v_mov_b32_e32 v0, 0
	s_addc_u32 s52, s27, 0
	s_mov_b32 s53, -2
	v_mov_b32_e32 v1, v0
	v_mov_b64_e32 v[2:3], 0
	v_mov_b64_e32 v[4:5], 0
	v_mov_b64_e32 v[6:7], 0
	v_mov_b64_e32 v[16:17], 0
	v_mov_b64_e32 v[18:19], 0
	v_mov_b64_e32 v[20:21], 0
	v_mov_b64_e32 v[22:23], 0
	v_mov_b64_e32 v[32:33], 0
	v_mov_b64_e32 v[34:35], 0
	v_mov_b64_e32 v[36:37], 0
	v_mov_b64_e32 v[38:39], 0
	v_mov_b64_e32 v[48:49], 0
	v_mov_b64_e32 v[50:51], 0
	v_mov_b64_e32 v[52:53], 0
	v_mov_b64_e32 v[54:55], 0
	v_mov_b64_e32 v[8:9], 0
	v_mov_b64_e32 v[10:11], 0
	v_mov_b64_e32 v[12:13], 0
	v_mov_b64_e32 v[14:15], 0
	v_mov_b64_e32 v[24:25], 0
	v_mov_b64_e32 v[26:27], 0
	v_mov_b64_e32 v[28:29], 0
	v_mov_b64_e32 v[30:31], 0
	v_mov_b64_e32 v[40:41], 0
	v_mov_b64_e32 v[42:43], 0
	v_mov_b64_e32 v[44:45], 0
	v_mov_b64_e32 v[46:47], 0
	v_mov_b64_e32 v[56:57], 0
	v_mov_b64_e32 v[58:59], 0
	v_mov_b64_e32 v[60:61], 0
	v_mov_b64_e32 v[62:63], 0
	v_mov_b64_e32 v[64:65], 0
	v_mov_b64_e32 v[66:67], 0
	v_mov_b64_e32 v[68:69], 0
	v_mov_b64_e32 v[70:71], 0
	v_mov_b64_e32 v[80:81], 0
	v_mov_b64_e32 v[82:83], 0
	v_mov_b64_e32 v[84:85], 0
	v_mov_b64_e32 v[86:87], 0
	v_mov_b64_e32 v[96:97], 0
	v_mov_b64_e32 v[98:99], 0
	v_mov_b64_e32 v[100:101], 0
	v_mov_b64_e32 v[102:103], 0
	v_mov_b64_e32 v[112:113], 0
	v_mov_b64_e32 v[114:115], 0
	v_mov_b64_e32 v[116:117], 0
	v_mov_b64_e32 v[118:119], 0
	v_mov_b64_e32 v[72:73], 0
	v_mov_b64_e32 v[74:75], 0
	v_mov_b64_e32 v[76:77], 0
	v_mov_b64_e32 v[78:79], 0
	v_mov_b64_e32 v[88:89], 0
	v_mov_b64_e32 v[90:91], 0
	v_mov_b64_e32 v[92:93], 0
	v_mov_b64_e32 v[94:95], 0
	v_mov_b64_e32 v[104:105], 0
	v_mov_b64_e32 v[106:107], 0
	v_mov_b64_e32 v[108:109], 0
	v_mov_b64_e32 v[110:111], 0
	v_mov_b64_e32 v[120:121], 0
	v_mov_b64_e32 v[122:123], 0
	v_mov_b64_e32 v[124:125], 0
	v_mov_b64_e32 v[126:127], 0
